# attention steady loop: removed no-op lgkmcnt waits, merged phase-B waits, dropped m0 save/restore around LDS-DMA
# speedup vs baseline: 1.0146x; 1.0146x over previous
.LBB0_479:
	v_add_u32_e32 v179, s16, v2
	ds_read_b64_tr_b16 v[198:199], v179 offset:24576
	ds_read_b64_tr_b16 v[200:201], v179 offset:25088
	v_add_f32_e32 v88, v68, v69
	v_add_f32_e32 v88, v70, v88
	v_add_f32_e32 v88, v71, v88
	v_add_f32_e32 v88, v72, v88
	v_add_f32_e32 v88, v73, v88
	v_cvt_pk_bf16_f32 v160, v68, v69
	v_cvt_pk_bf16_f32 v161, v70, v71
	v_mfma_f32_32x32x16_bf16 v[100:115], v[84:87], v[152:155], v[36:51]
	ds_read_b64_tr_b16 v[202:203], v179 offset:28672
	ds_read_b64_tr_b16 v[204:205], v179 offset:29184
	v_add_f32_e32 v68, v74, v88
	v_mfma_f32_32x32x16_bf16 v[84:99], v[168:171], v[152:155], v[36:51]
	v_add_f32_e32 v68, v75, v68
	v_add_f32_e32 v68, v76, v68
	v_add_f32_e32 v140, v77, v68
	v_cvt_pk_bf16_f32 v162, v72, v73
	v_cvt_pk_bf16_f32 v163, v74, v75
	ds_read_b64_tr_b16 v[68:69], v179 offset:25600
	ds_read_b64_tr_b16 v[70:71], v179 offset:26112
	v_add_f32_e32 v72, v78, v140
	v_add_f32_e32 v72, v79, v72
	v_add_f32_e32 v72, v80, v72
	v_add_f32_e32 v140, v81, v72
	v_cvt_pk_bf16_f32 v156, v76, v77
	v_cvt_pk_bf16_f32 v157, v78, v79
	v_mfma_f32_32x32x16_bf16 v[100:115], v[172:175], v[144:147], v[100:115]
	ds_read_b64_tr_b16 v[72:73], v179 offset:29696
	ds_read_b64_tr_b16 v[74:75], v179 offset:30208
	v_mfma_f32_32x32x16_bf16 v[84:99], v[164:167], v[144:147], v[84:99]
	v_add_f32_e32 v76, v82, v140
	v_add_f32_e32 v76, v83, v76
	v_add_f32_e32 v76, v52, v76
	v_add_f32_e32 v140, v53, v76
	v_cvt_pk_bf16_f32 v158, v80, v81
	v_cvt_pk_bf16_f32 v159, v82, v83
	ds_read_b64_tr_b16 v[76:77], v179 offset:26624
	ds_read_b64_tr_b16 v[78:79], v179 offset:27136
	v_add_f32_e32 v80, v54, v140
	v_add_f32_e32 v80, v55, v80
	v_add_f32_e32 v80, v56, v80
	v_add_f32_e32 v80, v57, v80
	v_cvt_pk_bf16_f32 v148, v52, v53
	v_cvt_pk_bf16_f32 v149, v54, v55
	v_mfma_f32_32x32x16_bf16 v[100:115], v[128:131], v[136:139], v[100:115]
	ds_read_b64_tr_b16 v[52:53], v179 offset:30720
	ds_read_b64_tr_b16 v[54:55], v179 offset:31232
	v_mfma_f32_32x32x16_bf16 v[84:99], v[124:127], v[136:139], v[84:99]
	v_add_f32_e32 v80, v58, v80
	v_add_f32_e32 v80, v59, v80
	v_add_f32_e32 v80, v60, v80
	v_add_f32_e32 v80, v61, v80
	v_cvt_pk_bf16_f32 v150, v56, v57
	v_cvt_pk_bf16_f32 v151, v58, v59
	ds_read_b64_tr_b16 v[56:57], v179 offset:27648
	ds_read_b64_tr_b16 v[58:59], v179 offset:28160
	v_add_f32_e32 v80, v62, v80
	v_add_f32_e32 v80, v63, v80
	v_add_f32_e32 v80, v64, v80
	v_add_f32_e32 v80, v65, v80
	v_cvt_pk_bf16_f32 v140, v60, v61
	v_cvt_pk_bf16_f32 v141, v62, v63
	v_mfma_f32_32x32x16_bf16 v[100:115], v[120:123], v[132:135], v[100:115]
	ds_read_b64_tr_b16 v[60:61], v179 offset:31744
	ds_read_b64_tr_b16 v[62:63], v179 offset:32256
	v_mfma_f32_32x32x16_bf16 v[84:99], v[116:119], v[132:135], v[84:99]
	v_add_f32_e32 v80, v66, v80
	v_add_f32_e32 v80, v67, v80
	v_add_f32_e32 v179, 0, v80
	v_cvt_pk_bf16_f32 v142, v64, v65
	v_cvt_pk_bf16_f32 v143, v66, v67
	s_add_i32 s16, s21, 0x4000
	s_and_b32 s16, s16, 0xfc000
	s_lshl_b32 s16, s16, 1
	v_lshl_add_u64 v[64:65], v[182:183], 0, s[16:17]
	s_add_i32 m0, s22, s9
	s_add_i32 s16, s20, 0xffff4000
	global_load_lds_dwordx4 v[64:65], off
	s_and_b32 s16, s16, 0xfc000
	s_lshl_b32 s16, s16, 1
	v_lshl_add_u64 v[64:65], v[180:181], 0, s[16:17]
	s_add_i32 m0, s15, s8
	s_nop 0
	global_load_lds_dwordx4 v[64:65], off
	s_waitcnt lgkmcnt(4)
	v_mfma_f32_32x32x16_bf16 v[4:19], v[160:163], v[198:201], v[4:19]
	v_exp_f32_e32 v100, v100
	v_exp_f32_e32 v101, v101
	v_exp_f32_e32 v102, v102
	v_exp_f32_e32 v103, v103
	v_mfma_f32_32x32x16_bf16 v[20:35], v[160:163], v[202:205], v[20:35]
	v_exp_f32_e32 v104, v104
	v_exp_f32_e32 v105, v105
	v_exp_f32_e32 v106, v106
	v_exp_f32_e32 v107, v107
	v_add_u32_e32 v80, s15, v189
	ds_read_b128 v[64:67], v80
	ds_read_b128 v[120:123], v80 offset:512
	v_mfma_f32_32x32x16_bf16 v[4:19], v[156:159], v[68:71], v[4:19]
	v_exp_f32_e32 v108, v108
	v_exp_f32_e32 v109, v109
	v_exp_f32_e32 v110, v110
	v_exp_f32_e32 v111, v111
	ds_read_b128 v[124:127], v80 offset:2048
	ds_read_b128 v[128:131], v80 offset:2560
	v_mfma_f32_32x32x16_bf16 v[20:35], v[156:159], v[72:75], v[20:35]
	v_exp_f32_e32 v112, v112
	v_exp_f32_e32 v113, v113
	v_exp_f32_e32 v114, v114
	v_exp_f32_e32 v115, v115
	ds_read_b128 v[164:167], v80 offset:4096
	ds_read_b128 v[168:171], v80 offset:4608
	v_mfma_f32_32x32x16_bf16 v[4:19], v[148:151], v[76:79], v[4:19]
	v_exp_f32_e32 v84, v84
	v_exp_f32_e32 v85, v85
	v_exp_f32_e32 v86, v86
	v_exp_f32_e32 v87, v87
	ds_read_b128 v[172:175], v80 offset:6144
	ds_read_b128 v[116:119], v80 offset:6656
	v_mfma_f32_32x32x16_bf16 v[20:35], v[148:151], v[52:55], v[20:35]
	v_exp_f32_e32 v88, v88
	v_exp_f32_e32 v89, v89
	v_exp_f32_e32 v90, v90
	v_exp_f32_e32 v91, v91
	s_waitcnt lgkmcnt(8)
	v_mfma_f32_32x32x16_bf16 v[4:19], v[140:143], v[56:59], v[4:19]
	v_exp_f32_e32 v92, v92
	v_exp_f32_e32 v93, v93
	v_exp_f32_e32 v94, v94
	v_exp_f32_e32 v95, v95
	v_mfma_f32_32x32x16_bf16 v[20:35], v[140:143], v[60:63], v[20:35]
	v_exp_f32_e32 v96, v96
	v_exp_f32_e32 v97, v97
	v_exp_f32_e32 v98, v98
	v_exp_f32_e32 v99, v99
	s_waitcnt vmcnt(2) lgkmcnt(0)
	s_barrier
;   #define RESC() do{ if(resc){ asm volatile("s_waitcnt lgkmcnt(0)":::"memory"); \
;       _Pragma("unroll") for(int d_=0;d_<2;++d_) _Pragma("unroll") for(int r=0;r<16;++r)o[d_][r]*=wsf[crow(r,hi)]; } }while(0)
;   #define ROT() do{sl_prev=sl_cur;sl_cur=sl_next;sl_next=(sl_next==(NSLOT-1)*SLOTB)?0:sl_next+SLOTB;}while(0)
;   #define WAIT_STEADY() WAIT_BAR(3)
;   #define WAIT_STEADY() WAIT_BAR(2)
; template<int THRL,bool NOMAX> __device__ __forceinline__ void attn_unit(int b,int h,int qb,int t0,const bf16*Q,const bf16*__restrict__ KV,const bf16*__restrict__ GA,bf16*O,char*shm){
;     ...
;   for(;t+5<NT;t+=2){
;     STEP(pB0,pB1,pA0,pA1,t,true,true,true);     WAIT_STEADY(); RESC(); ROT();
;     STEP(pA0,pA1,pB0,pB1,t+1,true,true,true);   WAIT_STEADY(); RESC(); ROT();
;   }
	s_add_i32 s16, s15, 0x2000
	s_cmpk_lg_i32 s15, 0x4000
	s_cselect_b32 s23, s16, 0
	v_add_u32_e32 v190, s22, v2
	ds_read_b64_tr_b16 v[198:199], v190 offset:24576
	ds_read_b64_tr_b16 v[200:201], v190 offset:25088
	v_mfma_f32_32x32x16_bf16 v[68:83], v[64:67], v[152:155], v[36:51]
	v_add_f32_e32 v52, v100, v101
	v_add_f32_e32 v52, v102, v52
	v_add_f32_e32 v52, v103, v52
	v_add_f32_e32 v52, v104, v52
	v_add_f32_e32 v52, v105, v52
	v_cvt_pk_bf16_f32 v160, v100, v101
	v_cvt_pk_bf16_f32 v161, v102, v103
	ds_read_b64_tr_b16 v[202:203], v190 offset:28672
	ds_read_b64_tr_b16 v[204:205], v190 offset:29184
	v_add_f32_e32 v52, v106, v52
	v_add_f32_e32 v52, v107, v52
	v_add_f32_e32 v52, v108, v52
	v_add_f32_e32 v140, v109, v52
	v_mfma_f32_32x32x16_bf16 v[52:67], v[120:123], v[152:155], v[36:51]
	v_cvt_pk_bf16_f32 v162, v104, v105
	v_cvt_pk_bf16_f32 v163, v106, v107
	ds_read_b64_tr_b16 v[100:101], v190 offset:25600
	ds_read_b64_tr_b16 v[102:103], v190 offset:26112
	v_mfma_f32_32x32x16_bf16 v[68:83], v[124:127], v[144:147], v[68:83]
	v_add_f32_e32 v104, v110, v140
	v_add_f32_e32 v104, v111, v104
	v_add_f32_e32 v104, v112, v104
	v_add_f32_e32 v120, v113, v104
	v_cvt_pk_bf16_f32 v156, v108, v109
	v_cvt_pk_bf16_f32 v157, v110, v111
	ds_read_b64_tr_b16 v[104:105], v190 offset:29696
	ds_read_b64_tr_b16 v[106:107], v190 offset:30208
	v_mfma_f32_32x32x16_bf16 v[52:67], v[128:131], v[144:147], v[52:67]
	v_add_f32_e32 v108, v114, v120
	v_add_f32_e32 v108, v115, v108
	v_add_f32_e32 v108, v84, v108
	v_add_f32_e32 v120, v85, v108
	v_cvt_pk_bf16_f32 v158, v112, v113
	v_cvt_pk_bf16_f32 v159, v114, v115
	ds_read_b64_tr_b16 v[108:109], v190 offset:26624
	ds_read_b64_tr_b16 v[110:111], v190 offset:27136
	v_mfma_f32_32x32x16_bf16 v[68:83], v[164:167], v[136:139], v[68:83]
	v_add_f32_e32 v112, v86, v120
	v_add_f32_e32 v112, v87, v112
	v_add_f32_e32 v112, v88, v112
	v_add_f32_e32 v120, v89, v112
	v_cvt_pk_bf16_f32 v148, v84, v85
	v_cvt_pk_bf16_f32 v149, v86, v87
	ds_read_b64_tr_b16 v[112:113], v190 offset:30720
	ds_read_b64_tr_b16 v[114:115], v190 offset:31232
	v_mfma_f32_32x32x16_bf16 v[52:67], v[168:171], v[136:139], v[52:67]
	v_add_f32_e32 v84, v90, v120
	v_add_f32_e32 v84, v91, v84
	v_add_f32_e32 v84, v92, v84
	v_add_f32_e32 v84, v93, v84
	v_cvt_pk_bf16_f32 v150, v88, v89
	v_cvt_pk_bf16_f32 v151, v90, v91
	ds_read_b64_tr_b16 v[88:89], v190 offset:27648
	ds_read_b64_tr_b16 v[90:91], v190 offset:28160
	v_mfma_f32_32x32x16_bf16 v[68:83], v[172:175], v[132:135], v[68:83]
	v_add_f32_e32 v84, v94, v84
	v_add_f32_e32 v84, v95, v84
	v_add_f32_e32 v84, v96, v84
	v_add_f32_e32 v84, v97, v84
	v_cvt_pk_bf16_f32 v140, v92, v93
	v_cvt_pk_bf16_f32 v141, v94, v95
	ds_read_b64_tr_b16 v[92:93], v190 offset:31744
	ds_read_b64_tr_b16 v[94:95], v190 offset:32256
	v_mfma_f32_32x32x16_bf16 v[52:67], v[116:119], v[132:135], v[52:67]
	v_add_f32_e32 v84, v98, v84
	v_add_f32_e32 v84, v99, v84
	v_add_f32_e32 v190, 0, v84
	v_cvt_pk_bf16_f32 v142, v96, v97
	v_cvt_pk_bf16_f32 v143, v98, v99
	s_and_b32 s16, s20, 0xfc000
	s_lshl_b32 s16, s16, 1
	v_lshl_add_u64 v[84:85], v[182:183], 0, s[16:17]
	s_add_i32 m0, s15, s9
	s_and_b32 s16, s21, 0xfc000
	global_load_lds_dwordx4 v[84:85], off
	s_lshl_b32 s16, s16, 1
	v_lshl_add_u64 v[84:85], v[180:181], 0, s[16:17]
	s_add_i32 m0, s23, s8
	s_nop 0
	global_load_lds_dwordx4 v[84:85], off
	s_waitcnt lgkmcnt(4)
	v_mfma_f32_32x32x16_bf16 v[4:19], v[160:163], v[198:201], v[4:19]
	v_exp_f32_e32 v68, v68
	v_exp_f32_e32 v69, v69
	v_exp_f32_e32 v70, v70
	v_exp_f32_e32 v71, v71
	v_mfma_f32_32x32x16_bf16 v[20:35], v[160:163], v[202:205], v[20:35]
	v_exp_f32_e32 v72, v72
	v_exp_f32_e32 v73, v73
	v_exp_f32_e32 v74, v74
	v_exp_f32_e32 v75, v75
	v_add_u32_e32 v96, s23, v189
	ds_read_b128 v[84:87], v96
	ds_read_b128 v[168:171], v96 offset:512
	v_mfma_f32_32x32x16_bf16 v[4:19], v[156:159], v[100:103], v[4:19]
	v_exp_f32_e32 v76, v76
	v_exp_f32_e32 v77, v77
	v_exp_f32_e32 v78, v78
	v_exp_f32_e32 v79, v79
	ds_read_b128 v[172:175], v96 offset:2048
	ds_read_b128 v[164:167], v96 offset:2560
	v_mfma_f32_32x32x16_bf16 v[20:35], v[156:159], v[104:107], v[20:35]
	v_exp_f32_e32 v80, v80
	v_exp_f32_e32 v81, v81
	v_exp_f32_e32 v82, v82
	v_exp_f32_e32 v83, v83
	ds_read_b128 v[128:131], v96 offset:4096
	ds_read_b128 v[124:127], v96 offset:4608
	v_mfma_f32_32x32x16_bf16 v[4:19], v[148:151], v[108:111], v[4:19]
	v_exp_f32_e32 v52, v52
	v_exp_f32_e32 v53, v53
	v_exp_f32_e32 v54, v54
	v_exp_f32_e32 v55, v55
	ds_read_b128 v[120:123], v96 offset:6144
	ds_read_b128 v[116:119], v96 offset:6656
	v_mfma_f32_32x32x16_bf16 v[20:35], v[148:151], v[112:115], v[20:35]
	v_exp_f32_e32 v56, v56
	v_exp_f32_e32 v57, v57
	v_exp_f32_e32 v58, v58
	v_exp_f32_e32 v59, v59
	s_waitcnt lgkmcnt(8)
	v_mfma_f32_32x32x16_bf16 v[4:19], v[140:143], v[88:91], v[4:19]
	v_exp_f32_e32 v60, v60
	v_exp_f32_e32 v61, v61
	v_exp_f32_e32 v62, v62
	v_exp_f32_e32 v63, v63
	v_mfma_f32_32x32x16_bf16 v[20:35], v[140:143], v[92:95], v[20:35]
	v_exp_f32_e32 v64, v64
	v_exp_f32_e32 v65, v65
	v_exp_f32_e32 v66, v66
	v_exp_f32_e32 v67, v67
	s_add_i32 s26, s23, 0x2000
	s_waitcnt vmcnt(2) lgkmcnt(0)
	s_barrier
	s_cmpk_lg_i32 s23, 0x4000
	v_add_f32_e32 v88, v191, v179
	s_mov_b32 s16, s15
	s_cselect_b32 s15, s26, 0
	s_add_i32 s14, s14, 2
	s_add_i32 s21, s21, 0x8000
	s_add_i32 s20, s20, 0x8000
	s_mov_b32 s22, s23
	v_add_f32_e32 v191, v88, v190
	s_cmp_gt_u32 s14, 56
	s_cbranch_scc0 .LBB0_479
;   #define RESC() do{ if(resc){ asm volatile("s_waitcnt lgkmcnt(0)":::"memory"); \
;       _Pragma("unroll") for(int d_=0;d_<2;++d_) _Pragma("unroll") for(int r=0;r<16;++r)o[d_][r]*=wsf[crow(r,hi)]; } }while(0)
;   #define ROT() do{sl_prev=sl_cur;sl_cur=sl_next;sl_next=(sl_next==(NSLOT-1)*SLOTB)?0:sl_next+SLOTB;}while(0)
;   #define ENDW(tt) do{ if((tt)+3<NT){WAIT_BAR(2);} else if((tt)+2<NT){WAIT_BAR(1);} else {WAIT_BAR(0);} }while(0)
; template<int THRL,bool NOMAX> __device__ __forceinline__ void attn_unit(int b,int h,int qb,int t0,const bf16*Q,const bf16*__restrict__ KV,const bf16*__restrict__ GA,bf16*O,char*shm){
;     ...
;   for(;t+1<NT;t+=2){
;     STEP(pB0,pB1,pA0,pA1,t,(t+3<NT),(t+1<NT),(t+1<NT));       ENDW(t);   RESC(); ROT();
;     STEP(pA0,pA1,pB0,pB1,t+1,(t+4<NT),(t+2<NT),(t+2<NT));     ENDW(t+1); RESC(); ROT();
;   }
	s_and_b32 s12, s12, 0x3fffffc0
	s_cmp_lg_u32 0, -1
	s_cselect_b32 s14, 0, 0
	s_add_i32 s15, s14, 0x6000
	s_lshl_b32 s12, s12, 2
	v_add_u32_e32 v88, s15, v177
	s_add_i32 s12, s12, 0
	v_add3_u32 v190, v88, v176, v178
	ds_read_b64_tr_b16 v[198:199], v2 offset:32768
	ds_read_b64_tr_b16 v[200:201], v2 offset:33280
	v_add_f32_e32 v88, v68, v69
	v_add_f32_e32 v88, v70, v88
	v_add_f32_e32 v88, v71, v88
	v_add_f32_e32 v88, v72, v88
	v_add_f32_e32 v88, v73, v88
	v_cvt_pk_bf16_f32 v160, v68, v69
	v_cvt_pk_bf16_f32 v161, v70, v71
	s_waitcnt lgkmcnt(9)
	v_mfma_f32_32x32x16_bf16 v[100:115], v[84:87], v[152:155], v[36:51]
	ds_read_b64_tr_b16 v[176:177], v2 offset:36864
	ds_read_b64_tr_b16 v[178:179], v2 offset:37376
	v_add_f32_e32 v68, v74, v88
	v_add_f32_e32 v68, v75, v68
	v_add_f32_e32 v68, v76, v68
	v_add_f32_e32 v140, v77, v68
	v_cvt_pk_bf16_f32 v162, v72, v73
	v_cvt_pk_bf16_f32 v163, v74, v75
	s_waitcnt lgkmcnt(10)
	v_mfma_f32_32x32x16_bf16 v[84:99], v[168:171], v[152:155], v[36:51]
	ds_read_b64_tr_b16 v[68:69], v2 offset:33792
	ds_read_b64_tr_b16 v[70:71], v2 offset:34304
	v_add_f32_e32 v72, v78, v140
	v_add_f32_e32 v72, v79, v72
	v_add_f32_e32 v72, v80, v72
	v_add_f32_e32 v140, v81, v72
	v_cvt_pk_bf16_f32 v156, v76, v77
	v_cvt_pk_bf16_f32 v157, v78, v79
	s_waitcnt lgkmcnt(11)
	v_mfma_f32_32x32x16_bf16 v[100:115], v[172:175], v[144:147], v[100:115]
	ds_read_b64_tr_b16 v[72:73], v2 offset:37888
	ds_read_b64_tr_b16 v[74:75], v2 offset:38400
	v_add_f32_e32 v76, v82, v140
	v_add_f32_e32 v76, v83, v76
	v_add_f32_e32 v76, v52, v76
	v_add_f32_e32 v140, v53, v76
	v_cvt_pk_bf16_f32 v158, v80, v81
	v_cvt_pk_bf16_f32 v159, v82, v83
	s_waitcnt lgkmcnt(12)
	v_mfma_f32_32x32x16_bf16 v[84:99], v[164:167], v[144:147], v[84:99]
	ds_read_b64_tr_b16 v[76:77], v2 offset:34816
	ds_read_b64_tr_b16 v[78:79], v2 offset:35328
	v_add_f32_e32 v80, v54, v140
	v_add_f32_e32 v80, v55, v80
	v_add_f32_e32 v80, v56, v80
	v_add_f32_e32 v80, v57, v80
	v_cvt_pk_bf16_f32 v148, v52, v53
	v_cvt_pk_bf16_f32 v149, v54, v55
	s_waitcnt lgkmcnt(13)
	v_mfma_f32_32x32x16_bf16 v[100:115], v[128:131], v[136:139], v[100:115]
	ds_read_b64_tr_b16 v[52:53], v2 offset:38912
	ds_read_b64_tr_b16 v[54:55], v2 offset:39424
	v_add_f32_e32 v80, v58, v80
	v_add_f32_e32 v80, v59, v80
	v_add_f32_e32 v80, v60, v80
	v_add_f32_e32 v80, v61, v80
	v_cvt_pk_bf16_f32 v150, v56, v57
	v_cvt_pk_bf16_f32 v151, v58, v59
	s_waitcnt lgkmcnt(14)
	v_mfma_f32_32x32x16_bf16 v[84:99], v[124:127], v[136:139], v[84:99]
	ds_read_b64_tr_b16 v[56:57], v2 offset:35840
	ds_read_b64_tr_b16 v[58:59], v2 offset:36352
	v_add_f32_e32 v80, v62, v80
	v_add_f32_e32 v80, v63, v80
	v_add_f32_e32 v80, v64, v80
	v_add_f32_e32 v80, v65, v80
	v_cvt_pk_bf16_f32 v140, v60, v61
	v_cvt_pk_bf16_f32 v141, v62, v63
	s_waitcnt lgkmcnt(14)
	v_mfma_f32_32x32x16_bf16 v[100:115], v[120:123], v[132:135], v[100:115]
	ds_read_b64_tr_b16 v[60:61], v2 offset:39936
	ds_read_b64_tr_b16 v[62:63], v2 offset:40448
	v_add_f32_e32 v80, v66, v80
	v_add_f32_e32 v80, v67, v80
	v_add_f32_e32 v80, 0, v80
	v_cvt_pk_bf16_f32 v142, v64, v65
	v_cvt_pk_bf16_f32 v143, v66, v67
	v_mfma_f32_32x32x16_bf16 v[84:99], v[116:119], v[132:135], v[84:99]
	v_readlane_b32 s20, v254, 56
	v_readlane_b32 s21, v254, 57
	s_mov_b32 s21, s17
	s_add_i32 s13, s14, s13
	v_lshl_add_u64 v[64:65], v[182:183], 0, s[20:21]
	s_add_i32 s14, s13, 0x4000
	s_mov_b32 s15, m0
	s_mov_b32 m0, s14
	s_nop 0
	global_load_lds_dwordx4 v[64:65], off
	s_mov_b32 m0, s15
	v_add_f32_e32 v191, v191, v80
	v_readlane_b32 s14, v254, 58
	v_readlane_b32 s15, v254, 59
	s_mov_b32 s15, s17
	s_mov_b32 s16, s14
	v_lshl_add_u64 v[64:65], v[180:181], 0, s[14:15]
	s_mov_b32 s14, m0
	s_mov_b32 m0, s8
	s_nop 0
	global_load_lds_dwordx4 v[64:65], off
	s_mov_b32 m0, s14
	v_writelane_b32 v254, s16, 58
	s_nop 1
	v_writelane_b32 v254, s17, 59
	s_waitcnt lgkmcnt(14)
	v_mfma_f32_32x32x16_bf16 v[4:19], v[160:163], v[198:201], v[4:19]
	v_exp_f32_e32 v100, v100
	v_exp_f32_e32 v101, v101
	v_exp_f32_e32 v102, v102
	v_exp_f32_e32 v103, v103
	s_waitcnt lgkmcnt(12)
	v_mfma_f32_32x32x16_bf16 v[20:35], v[160:163], v[176:179], v[20:35]
	v_exp_f32_e32 v104, v104
	v_exp_f32_e32 v105, v105
	v_exp_f32_e32 v106, v106
	v_exp_f32_e32 v107, v107
	ds_read_b128 v[64:67], v189
	ds_read_b128 v[80:83], v189 offset:512
	s_waitcnt lgkmcnt(12)
	v_mfma_f32_32x32x16_bf16 v[4:19], v[156:159], v[68:71], v[4:19]
	v_exp_f32_e32 v108, v108
	v_exp_f32_e32 v109, v109
	v_exp_f32_e32 v110, v110
	v_exp_f32_e32 v111, v111
	ds_read_b128 v[164:167], v189 offset:2048
	ds_read_b128 v[168:171], v189 offset:2560
	s_waitcnt lgkmcnt(12)
	v_mfma_f32_32x32x16_bf16 v[20:35], v[156:159], v[72:75], v[20:35]
	v_exp_f32_e32 v112, v112
	v_exp_f32_e32 v113, v113
	v_exp_f32_e32 v114, v114
	v_exp_f32_e32 v115, v115
	ds_read_b128 v[172:175], v189 offset:4096
	ds_read_b128 v[176:179], v189 offset:4608
	s_waitcnt lgkmcnt(12)
	v_mfma_f32_32x32x16_bf16 v[4:19], v[148:151], v[76:79], v[4:19]
	v_exp_f32_e32 v84, v84
	v_exp_f32_e32 v85, v85
	v_exp_f32_e32 v86, v86
	v_exp_f32_e32 v87, v87
	ds_read_b128 v[198:201], v189 offset:6144
	ds_read_b128 v[72:75], v189 offset:6656
	s_waitcnt lgkmcnt(12)
	v_mfma_f32_32x32x16_bf16 v[20:35], v[148:151], v[52:55], v[20:35]
	v_exp_f32_e32 v88, v88
	v_exp_f32_e32 v89, v89
	v_exp_f32_e32 v90, v90
	v_exp_f32_e32 v91, v91
	s_waitcnt lgkmcnt(10)
	v_mfma_f32_32x32x16_bf16 v[4:19], v[140:143], v[56:59], v[4:19]
	v_exp_f32_e32 v92, v92
	v_exp_f32_e32 v93, v93
	v_exp_f32_e32 v94, v94
	v_exp_f32_e32 v95, v95
	s_waitcnt lgkmcnt(8)
	v_mfma_f32_32x32x16_bf16 v[20:35], v[140:143], v[60:63], v[20:35]
	v_exp_f32_e32 v96, v96
	v_exp_f32_e32 v97, v97
	v_exp_f32_e32 v98, v98
	v_exp_f32_e32 v99, v99
	s_waitcnt vmcnt(2) lgkmcnt(0)
	s_barrier
;   #define RESC() do{ if(resc){ asm volatile("s_waitcnt lgkmcnt(0)":::"memory"); \
;       _Pragma("unroll") for(int d_=0;d_<2;++d_) _Pragma("unroll") for(int r=0;r<16;++r)o[d_][r]*=wsf[crow(r,hi)]; } }while(0)
;   #define ROT() do{sl_prev=sl_cur;sl_cur=sl_next;sl_next=(sl_next==(NSLOT-1)*SLOTB)?0:sl_next+SLOTB;}while(0)
;   #define ENDW(tt) do{ if((tt)+3<NT){WAIT_BAR(2);} else if((tt)+2<NT){WAIT_BAR(1);} else {WAIT_BAR(0);} }while(0)
; template<int THRL,bool NOMAX> __device__ __forceinline__ void attn_unit(int b,int h,int qb,int t0,const bf16*Q,const bf16*__restrict__ KV,const bf16*__restrict__ GA,bf16*O,char*shm){
;     ...
;   for(;t+1<NT;t+=2){
;     STEP(pB0,pB1,pA0,pA1,t,(t+3<NT),(t+1<NT),(t+1<NT));       ENDW(t);   RESC(); ROT();
;     STEP(pA0,pA1,pB0,pB1,t+1,(t+4<NT),(t+2<NT),(t+2<NT));     ENDW(t+1); RESC(); ROT();
;   }
	ds_read_b64_tr_b16 v[202:203], v2 offset:40960
	ds_read_b64_tr_b16 v[204:205], v2 offset:41472
	v_add_f32_e32 v52, v100, v101
	v_add_f32_e32 v52, v102, v52
	v_add_f32_e32 v52, v103, v52
	v_add_f32_e32 v52, v104, v52
	v_add_f32_e32 v52, v105, v52
	v_cvt_pk_bf16_f32 v160, v100, v101
	v_cvt_pk_bf16_f32 v161, v102, v103
	s_waitcnt lgkmcnt(9)
	v_mfma_f32_32x32x16_bf16 v[116:131], v[64:67], v[152:155], v[36:51]
	ds_read_b64_tr_b16 v[100:101], v2 offset:45056
	ds_read_b64_tr_b16 v[102:103], v2 offset:45568
	v_add_f32_e32 v52, v106, v52
	v_add_f32_e32 v52, v107, v52
	v_add_f32_e32 v52, v108, v52
	v_add_f32_e32 v76, v109, v52
	v_cvt_pk_bf16_f32 v162, v104, v105
	v_cvt_pk_bf16_f32 v163, v106, v107
	s_waitcnt lgkmcnt(10)
	v_mfma_f32_32x32x16_bf16 v[52:67], v[80:83], v[152:155], v[36:51]
	ds_read_b64_tr_b16 v[68:69], v2 offset:41984
	ds_read_b64_tr_b16 v[70:71], v2 offset:42496
	v_add_f32_e32 v76, v110, v76
	v_add_f32_e32 v76, v111, v76
	v_add_f32_e32 v76, v112, v76
	v_add_f32_e32 v80, v113, v76
	v_cvt_pk_bf16_f32 v156, v108, v109
	v_cvt_pk_bf16_f32 v157, v110, v111
	s_waitcnt lgkmcnt(11)
	v_mfma_f32_32x32x16_bf16 v[116:131], v[164:167], v[144:147], v[116:131]
	ds_read_b64_tr_b16 v[76:77], v2 offset:46080
	ds_read_b64_tr_b16 v[78:79], v2 offset:46592
	v_add_f32_e32 v80, v114, v80
	v_add_f32_e32 v80, v115, v80
	v_add_f32_e32 v80, v84, v80
	v_add_f32_e32 v104, v85, v80
	v_cvt_pk_bf16_f32 v158, v112, v113
	v_cvt_pk_bf16_f32 v159, v114, v115
	s_waitcnt lgkmcnt(12)
	v_mfma_f32_32x32x16_bf16 v[52:67], v[168:171], v[144:147], v[52:67]
	ds_read_b64_tr_b16 v[80:81], v2 offset:43008
	ds_read_b64_tr_b16 v[82:83], v2 offset:43520
	v_add_f32_e32 v104, v86, v104
	v_add_f32_e32 v104, v87, v104
	v_add_f32_e32 v104, v88, v104
	v_add_f32_e32 v108, v89, v104
	v_cvt_pk_bf16_f32 v148, v84, v85
	v_cvt_pk_bf16_f32 v149, v86, v87
	s_waitcnt lgkmcnt(13)
	v_mfma_f32_32x32x16_bf16 v[116:131], v[172:175], v[136:139], v[116:131]
	ds_read_b64_tr_b16 v[104:105], v2 offset:47104
	ds_read_b64_tr_b16 v[106:107], v2 offset:47616
	v_add_f32_e32 v84, v90, v108
	v_add_f32_e32 v84, v91, v84
	v_add_f32_e32 v84, v92, v84
	v_add_f32_e32 v84, v93, v84
	v_cvt_pk_bf16_f32 v150, v88, v89
	v_cvt_pk_bf16_f32 v151, v90, v91
	s_waitcnt lgkmcnt(14)
	v_mfma_f32_32x32x16_bf16 v[52:67], v[176:179], v[136:139], v[52:67]
	ds_read_b64_tr_b16 v[88:89], v2 offset:44032
	ds_read_b64_tr_b16 v[90:91], v2 offset:44544
	v_add_f32_e32 v84, v94, v84
	v_add_f32_e32 v84, v95, v84
	v_add_f32_e32 v84, v96, v84
	v_add_f32_e32 v84, v97, v84
	v_cvt_pk_bf16_f32 v140, v92, v93
	v_cvt_pk_bf16_f32 v141, v94, v95
	s_waitcnt lgkmcnt(14)
	v_mfma_f32_32x32x16_bf16 v[116:131], v[198:201], v[132:135], v[116:131]
	ds_read_b64_tr_b16 v[92:93], v2 offset:48128
	ds_read_b64_tr_b16 v[94:95], v2 offset:48640
	v_mfma_f32_32x32x16_bf16 v[52:67], v[72:75], v[132:135], v[52:67]
	v_add_f32_e32 v72, v98, v84
	v_add_f32_e32 v72, v99, v72
	v_add_f32_e32 v72, 0, v72
	v_cvt_pk_bf16_f32 v142, v96, v97
	v_cvt_pk_bf16_f32 v143, v98, v99
	v_readlane_b32 s22, v254, 60
	v_readlane_b32 s23, v254, 61
	s_mov_b32 s23, s17
	v_add_f32_e32 v191, v191, v72
	v_lshl_add_u64 v[72:73], v[182:183], 0, s[22:23]
	s_mov_b32 s14, m0
	s_mov_b32 m0, s9
	s_nop 0
	global_load_lds_dwordx4 v[72:73], off
	s_mov_b32 m0, s14
	s_add_i32 s9, s13, 0x8000
	v_readlane_b32 s14, v254, 62
	v_readlane_b32 s15, v254, 63
	s_mov_b32 s15, s17
	s_mov_b32 s16, s14
	v_lshl_add_u64 v[72:73], v[180:181], 0, s[14:15]
	s_mov_b32 s14, m0
	s_mov_b32 m0, s9
	s_nop 0
	global_load_lds_dwordx4 v[72:73], off
	s_mov_b32 m0, s14
	v_writelane_b32 v254, s16, 62
	s_nop 1
	v_writelane_b32 v254, s17, 63
	s_waitcnt lgkmcnt(14)
	v_mfma_f32_32x32x16_bf16 v[4:19], v[160:163], v[202:205], v[4:19]
	v_exp_f32_e32 v116, v116
	v_exp_f32_e32 v117, v117
	v_exp_f32_e32 v118, v118
	v_exp_f32_e32 v119, v119
	s_waitcnt lgkmcnt(12)
	v_mfma_f32_32x32x16_bf16 v[20:35], v[160:163], v[100:103], v[20:35]
	v_exp_f32_e32 v120, v120
	v_exp_f32_e32 v121, v121
	v_exp_f32_e32 v122, v122
	v_exp_f32_e32 v123, v123
	ds_read_b128 v[72:75], v189 offset:8192
	ds_read_b128 v[96:99], v189 offset:8704
	s_waitcnt lgkmcnt(12)
	v_mfma_f32_32x32x16_bf16 v[4:19], v[156:159], v[68:71], v[4:19]
	v_exp_f32_e32 v124, v124
	v_exp_f32_e32 v125, v125
	v_exp_f32_e32 v126, v126
	v_exp_f32_e32 v127, v127
	ds_read_b128 v[164:167], v189 offset:10240
	ds_read_b128 v[168:171], v189 offset:10752
	s_waitcnt lgkmcnt(12)
	v_mfma_f32_32x32x16_bf16 v[20:35], v[156:159], v[76:79], v[20:35]
	v_exp_f32_e32 v128, v128
	v_exp_f32_e32 v129, v129
	v_exp_f32_e32 v130, v130
	v_exp_f32_e32 v131, v131
	ds_read_b128 v[172:175], v189 offset:12288
	ds_read_b128 v[176:179], v189 offset:12800
	s_waitcnt lgkmcnt(12)
	v_mfma_f32_32x32x16_bf16 v[4:19], v[148:151], v[80:83], v[4:19]
	v_exp_f32_e32 v52, v52
	v_exp_f32_e32 v53, v53
	v_exp_f32_e32 v54, v54
	v_exp_f32_e32 v55, v55
	ds_read_b128 v[198:201], v189 offset:14336
	ds_read_b128 v[84:87], v189 offset:14848
	s_waitcnt lgkmcnt(12)
	v_mfma_f32_32x32x16_bf16 v[20:35], v[148:151], v[104:107], v[20:35]
	v_exp_f32_e32 v56, v56
	v_exp_f32_e32 v57, v57
	v_exp_f32_e32 v58, v58
	v_exp_f32_e32 v59, v59
	s_waitcnt lgkmcnt(10)
	v_mfma_f32_32x32x16_bf16 v[4:19], v[140:143], v[88:91], v[4:19]
	v_exp_f32_e32 v60, v60
	v_exp_f32_e32 v61, v61
	v_exp_f32_e32 v62, v62
	v_exp_f32_e32 v63, v63
	s_waitcnt lgkmcnt(8)
	v_mfma_f32_32x32x16_bf16 v[20:35], v[140:143], v[92:95], v[20:35]
	v_exp_f32_e32 v64, v64
	v_exp_f32_e32 v65, v65
	v_exp_f32_e32 v66, v66
	v_exp_f32_e32 v67, v67
	s_waitcnt vmcnt(2) lgkmcnt(0)
	s_barrier
;   #define RESC() do{ if(resc){ asm volatile("s_waitcnt lgkmcnt(0)":::"memory"); \
;       _Pragma("unroll") for(int d_=0;d_<2;++d_) _Pragma("unroll") for(int r=0;r<16;++r)o[d_][r]*=wsf[crow(r,hi)]; } }while(0)
;   #define ROT() do{sl_prev=sl_cur;sl_cur=sl_next;sl_next=(sl_next==(NSLOT-1)*SLOTB)?0:sl_next+SLOTB;}while(0)
;   #define ENDW(tt) do{ if((tt)+3<NT){WAIT_BAR(2);} else if((tt)+2<NT){WAIT_BAR(1);} else {WAIT_BAR(0);} }while(0)
; template<int THRL,bool NOMAX> __device__ __forceinline__ void attn_unit(int b,int h,int qb,int t0,const bf16*Q,const bf16*__restrict__ KV,const bf16*__restrict__ GA,bf16*O,char*shm){
;     ...
;   for(;t+1<NT;t+=2){
;     STEP(pB0,pB1,pA0,pA1,t,(t+3<NT),(t+1<NT),(t+1<NT));       ENDW(t);   RESC(); ROT();
;     STEP(pA0,pA1,pB0,pB1,t+1,(t+4<NT),(t+2<NT),(t+2<NT));     ENDW(t+1); RESC(); ROT();
;   }
	ds_read_b64_tr_b16 v[88:89], v2 offset:24576
	ds_read_b64_tr_b16 v[90:91], v2 offset:25088
	v_add_f32_e32 v68, v116, v117
	v_add_f32_e32 v68, v118, v68
	v_add_f32_e32 v68, v119, v68
	v_add_f32_e32 v68, v120, v68
	v_add_f32_e32 v68, v121, v68
	v_cvt_pk_bf16_f32 v160, v116, v117
	v_cvt_pk_bf16_f32 v161, v118, v119
	s_waitcnt lgkmcnt(9)
	v_mfma_f32_32x32x16_bf16 v[100:115], v[72:75], v[152:155], v[36:51]
	ds_read_b64_tr_b16 v[92:93], v2 offset:28672
	ds_read_b64_tr_b16 v[94:95], v2 offset:29184
	v_add_f32_e32 v68, v122, v68
	v_add_f32_e32 v68, v123, v68
	v_add_f32_e32 v68, v124, v68
	v_add_f32_e32 v116, v125, v68
	v_cvt_pk_bf16_f32 v162, v120, v121
	v_cvt_pk_bf16_f32 v163, v122, v123
	s_waitcnt lgkmcnt(10)
	v_mfma_f32_32x32x16_bf16 v[68:83], v[96:99], v[152:155], v[36:51]
	ds_read_b64_tr_b16 v[96:97], v2 offset:25600
	ds_read_b64_tr_b16 v[98:99], v2 offset:26112
	v_add_f32_e32 v116, v126, v116
	v_add_f32_e32 v116, v127, v116
	v_add_f32_e32 v116, v128, v116
	v_add_f32_e32 v120, v129, v116
	v_cvt_pk_bf16_f32 v156, v124, v125
	v_cvt_pk_bf16_f32 v157, v126, v127
	s_waitcnt lgkmcnt(11)
	v_mfma_f32_32x32x16_bf16 v[100:115], v[164:167], v[144:147], v[100:115]
	ds_read_b64_tr_b16 v[116:117], v2 offset:29696
	ds_read_b64_tr_b16 v[118:119], v2 offset:30208
	v_add_f32_e32 v120, v130, v120
	v_add_f32_e32 v120, v131, v120
	v_add_f32_e32 v120, v52, v120
	v_add_f32_e32 v124, v53, v120
	v_cvt_pk_bf16_f32 v158, v128, v129
	v_cvt_pk_bf16_f32 v159, v130, v131
	s_waitcnt lgkmcnt(12)
	v_mfma_f32_32x32x16_bf16 v[68:83], v[168:171], v[144:147], v[68:83]
	ds_read_b64_tr_b16 v[120:121], v2 offset:26624
	ds_read_b64_tr_b16 v[122:123], v2 offset:27136
	v_add_f32_e32 v124, v54, v124
	v_add_f32_e32 v124, v55, v124
	v_add_f32_e32 v124, v56, v124
	v_add_f32_e32 v124, v57, v124
	v_cvt_pk_bf16_f32 v148, v52, v53
	v_cvt_pk_bf16_f32 v149, v54, v55
	s_waitcnt lgkmcnt(13)
	v_mfma_f32_32x32x16_bf16 v[100:115], v[172:175], v[136:139], v[100:115]
	ds_read_b64_tr_b16 v[52:53], v2 offset:30720
	ds_read_b64_tr_b16 v[54:55], v2 offset:31232
	v_add_f32_e32 v124, v58, v124
	v_add_f32_e32 v124, v59, v124
	v_add_f32_e32 v124, v60, v124
	v_add_f32_e32 v124, v61, v124
	v_cvt_pk_bf16_f32 v150, v56, v57
	v_cvt_pk_bf16_f32 v151, v58, v59
	s_waitcnt lgkmcnt(14)
	v_mfma_f32_32x32x16_bf16 v[68:83], v[176:179], v[136:139], v[68:83]
	ds_read_b64_tr_b16 v[56:57], v2 offset:27648
	ds_read_b64_tr_b16 v[58:59], v2 offset:28160
	v_add_f32_e32 v124, v62, v124
	v_add_f32_e32 v124, v63, v124
	v_add_f32_e32 v124, v64, v124
	v_add_f32_e32 v124, v65, v124
	v_cvt_pk_bf16_f32 v140, v60, v61
	v_cvt_pk_bf16_f32 v141, v62, v63
	s_waitcnt lgkmcnt(14)
	v_mfma_f32_32x32x16_bf16 v[100:115], v[198:201], v[132:135], v[100:115]
	ds_read_b64_tr_b16 v[60:61], v2 offset:31744
	ds_read_b64_tr_b16 v[62:63], v2 offset:32256
	v_mfma_f32_32x32x16_bf16 v[68:83], v[84:87], v[132:135], v[68:83]
	v_add_f32_e32 v84, v66, v124
	v_add_f32_e32 v84, v67, v84
	v_add_f32_e32 v84, 0, v84
	v_cvt_pk_bf16_f32 v142, v64, v65
	v_cvt_pk_bf16_f32 v143, v66, v67
	s_mov_b32 s14, s20
	v_lshl_add_u64 v[64:65], v[180:181], 0, s[20:21]
	s_add_i32 s13, s13, 0xa000
	s_mov_b32 s9, m0
	s_mov_b32 m0, s13
	s_nop 0
	global_load_lds_dwordx4 v[64:65], off
	s_mov_b32 m0, s9
	v_writelane_b32 v254, s14, 56
	v_add_f32_e32 v182, v191, v84
	s_nop 0
	v_writelane_b32 v254, s15, 57
	s_waitcnt lgkmcnt(14)
	v_mfma_f32_32x32x16_bf16 v[4:19], v[160:163], v[88:91], v[4:19]
	v_exp_f32_e32 v100, v100
	v_exp_f32_e32 v101, v101
	v_exp_f32_e32 v102, v102
	v_exp_f32_e32 v103, v103
	s_waitcnt lgkmcnt(12)
	v_mfma_f32_32x32x16_bf16 v[20:35], v[160:163], v[92:95], v[20:35]
	v_exp_f32_e32 v104, v104
	v_exp_f32_e32 v105, v105
	v_exp_f32_e32 v106, v106
	v_exp_f32_e32 v107, v107
	ds_read_b128 v[64:67], v189 offset:16384
	ds_read_b128 v[124:127], v189 offset:16896
	s_waitcnt lgkmcnt(12)
	v_mfma_f32_32x32x16_bf16 v[4:19], v[156:159], v[96:99], v[4:19]
	v_exp_f32_e32 v108, v108
	v_exp_f32_e32 v109, v109
	v_exp_f32_e32 v110, v110
	v_exp_f32_e32 v111, v111
	ds_read_b128 v[128:131], v189 offset:18432
	ds_read_b128 v[164:167], v189 offset:18944
	s_waitcnt lgkmcnt(12)
	v_mfma_f32_32x32x16_bf16 v[20:35], v[156:159], v[116:119], v[20:35]
	v_exp_f32_e32 v112, v112
	v_exp_f32_e32 v113, v113
	v_exp_f32_e32 v114, v114
	v_exp_f32_e32 v115, v115
	ds_read_b128 v[168:171], v189 offset:20480
	ds_read_b128 v[172:175], v189 offset:20992
	s_waitcnt lgkmcnt(12)
	v_mfma_f32_32x32x16_bf16 v[4:19], v[148:151], v[120:123], v[4:19]
	v_exp_f32_e32 v68, v68
	v_exp_f32_e32 v69, v69
	v_exp_f32_e32 v70, v70
	v_exp_f32_e32 v71, v71
	ds_read_b128 v[120:123], v189 offset:22528
	ds_read_b128 v[116:119], v189 offset:23040
	s_waitcnt lgkmcnt(12)
	v_mfma_f32_32x32x16_bf16 v[20:35], v[148:151], v[52:55], v[20:35]
	v_exp_f32_e32 v72, v72
	v_exp_f32_e32 v73, v73
	v_exp_f32_e32 v74, v74
	v_exp_f32_e32 v75, v75
	s_waitcnt lgkmcnt(10)
	v_mfma_f32_32x32x16_bf16 v[4:19], v[140:143], v[56:59], v[4:19]
	v_exp_f32_e32 v76, v76
	v_exp_f32_e32 v77, v77
	v_exp_f32_e32 v78, v78
	v_exp_f32_e32 v79, v79
	s_waitcnt lgkmcnt(8)
	v_mfma_f32_32x32x16_bf16 v[20:35], v[140:143], v[60:63], v[20:35]
	v_exp_f32_e32 v80, v80
	v_exp_f32_e32 v81, v81
	v_exp_f32_e32 v82, v82
	v_exp_f32_e32 v83, v83
	s_waitcnt vmcnt(1) lgkmcnt(0)
	s_barrier
;   #define RESC() do{ if(resc){ asm volatile("s_waitcnt lgkmcnt(0)":::"memory"); \
;       _Pragma("unroll") for(int d_=0;d_<2;++d_) _Pragma("unroll") for(int r=0;r<16;++r)o[d_][r]*=wsf[crow(r,hi)]; } }while(0)
;   #define ROT() do{sl_prev=sl_cur;sl_cur=sl_next;sl_next=(sl_next==(NSLOT-1)*SLOTB)?0:sl_next+SLOTB;}while(0)
;   #define ENDW(tt) do{ if((tt)+3<NT){WAIT_BAR(2);} else if((tt)+2<NT){WAIT_BAR(1);} else {WAIT_BAR(0);} }while(0)
; template<int THRL,bool NOMAX> __device__ __forceinline__ void attn_unit(int b,int h,int qb,int t0,const bf16*Q,const bf16*__restrict__ KV,const bf16*__restrict__ GA,bf16*O,char*shm){
;     ...
;   for(;t+1<NT;t+=2){
;     STEP(pB0,pB1,pA0,pA1,t,(t+3<NT),(t+1<NT),(t+1<NT));       ENDW(t);   RESC(); ROT();
;     STEP(pA0,pA1,pB0,pB1,t+1,(t+4<NT),(t+2<NT),(t+2<NT));     ENDW(t+1); RESC(); ROT();
;   }
	ds_read_b64_tr_b16 v[176:177], v2 offset:32768
	ds_read_b64_tr_b16 v[178:179], v2 offset:33280
	v_add_f32_e32 v52, v100, v101
	v_add_f32_e32 v52, v102, v52
	v_add_f32_e32 v52, v103, v52
	v_add_f32_e32 v52, v104, v52
	v_add_f32_e32 v52, v105, v52
	v_cvt_pk_bf16_f32 v160, v100, v101
	v_cvt_pk_bf16_f32 v161, v102, v103
	s_waitcnt lgkmcnt(9)
	v_mfma_f32_32x32x16_bf16 v[84:99], v[64:67], v[152:155], v[36:51]
	ds_read_b64_tr_b16 v[100:101], v2 offset:36864
	ds_read_b64_tr_b16 v[102:103], v2 offset:37376
	v_add_f32_e32 v52, v106, v52
	v_add_f32_e32 v52, v107, v52
	v_add_f32_e32 v52, v108, v52
	v_add_f32_e32 v140, v109, v52
	v_cvt_pk_bf16_f32 v162, v104, v105
	v_cvt_pk_bf16_f32 v163, v106, v107
	s_waitcnt lgkmcnt(10)
	v_mfma_f32_32x32x16_bf16 v[52:67], v[124:127], v[152:155], v[36:51]
	ds_read_b64_tr_b16 v[124:125], v2 offset:33792
	ds_read_b64_tr_b16 v[126:127], v2 offset:34304
	v_add_f32_e32 v104, v110, v140
	v_add_f32_e32 v104, v111, v104
	v_add_f32_e32 v104, v112, v104
	v_add_f32_e32 v104, v113, v104
	v_cvt_pk_bf16_f32 v156, v108, v109
	v_cvt_pk_bf16_f32 v157, v110, v111
	s_waitcnt lgkmcnt(11)
	v_mfma_f32_32x32x16_bf16 v[84:99], v[128:131], v[144:147], v[84:99]
	ds_read_b64_tr_b16 v[106:107], v2 offset:37888
	ds_read_b64_tr_b16 v[108:109], v2 offset:38400
	v_add_f32_e32 v104, v114, v104
	v_add_f32_e32 v104, v115, v104
	v_add_f32_e32 v104, v68, v104
	v_add_f32_e32 v104, v69, v104
	v_cvt_pk_bf16_f32 v158, v112, v113
	v_cvt_pk_bf16_f32 v159, v114, v115
	s_waitcnt lgkmcnt(12)
	v_mfma_f32_32x32x16_bf16 v[52:67], v[164:167], v[144:147], v[52:67]
	ds_read_b64_tr_b16 v[110:111], v2 offset:34816
	ds_read_b64_tr_b16 v[112:113], v2 offset:35328
	v_add_f32_e32 v104, v70, v104
	v_add_f32_e32 v104, v71, v104
	v_add_f32_e32 v104, v72, v104
	v_add_f32_e32 v104, v73, v104
	v_cvt_pk_bf16_f32 v148, v68, v69
	v_cvt_pk_bf16_f32 v149, v70, v71
	s_waitcnt lgkmcnt(13)
	v_mfma_f32_32x32x16_bf16 v[84:99], v[168:171], v[136:139], v[84:99]
	ds_read_b64_tr_b16 v[68:69], v2 offset:38912
	ds_read_b64_tr_b16 v[70:71], v2 offset:39424
	v_add_f32_e32 v104, v74, v104
	v_add_f32_e32 v104, v75, v104
	v_add_f32_e32 v104, v76, v104
	v_add_f32_e32 v104, v77, v104
	v_cvt_pk_bf16_f32 v150, v72, v73
	v_cvt_pk_bf16_f32 v151, v74, v75
	s_waitcnt lgkmcnt(14)
	v_mfma_f32_32x32x16_bf16 v[52:67], v[172:175], v[136:139], v[52:67]
	ds_read_b64_tr_b16 v[72:73], v2 offset:35840
	ds_read_b64_tr_b16 v[74:75], v2 offset:36352
	v_add_f32_e32 v104, v78, v104
	v_add_f32_e32 v104, v79, v104
	v_add_f32_e32 v104, v80, v104
	v_add_f32_e32 v104, v81, v104
	v_cvt_pk_bf16_f32 v140, v76, v77
	v_cvt_pk_bf16_f32 v141, v78, v79
	s_waitcnt lgkmcnt(14)
	v_mfma_f32_32x32x16_bf16 v[84:99], v[120:123], v[132:135], v[84:99]
	ds_read_b64_tr_b16 v[76:77], v2 offset:39936
	ds_read_b64_tr_b16 v[78:79], v2 offset:40448
	v_add_f32_e32 v104, v82, v104
	v_add_f32_e32 v104, v83, v104
	v_add_f32_e32 v104, 0, v104
	v_cvt_pk_bf16_f32 v142, v80, v81
	v_cvt_pk_bf16_f32 v143, v82, v83
	v_mfma_f32_32x32x16_bf16 v[52:67], v[116:119], v[132:135], v[52:67]
	s_mov_b32 s14, s22
	v_lshl_add_u64 v[80:81], v[180:181], 0, s[22:23]
	s_mov_b32 s9, m0
	s_mov_b32 m0, s8
	s_nop 0
	global_load_lds_dwordx4 v[80:81], off
	s_mov_b32 m0, s9
	v_writelane_b32 v254, s14, 60
	v_add_f32_e32 v104, v182, v104
	s_nop 0
	v_writelane_b32 v254, s15, 61
	s_waitcnt lgkmcnt(14)
	v_mfma_f32_32x32x16_bf16 v[4:19], v[160:163], v[176:179], v[4:19]
	v_exp_f32_e32 v84, v84
	v_exp_f32_e32 v85, v85
	v_exp_f32_e32 v86, v86
	v_exp_f32_e32 v87, v87
	s_waitcnt lgkmcnt(12)
	v_mfma_f32_32x32x16_bf16 v[20:35], v[160:163], v[100:103], v[20:35]
	v_exp_f32_e32 v88, v88
	v_exp_f32_e32 v89, v89
	v_exp_f32_e32 v90, v90
	v_exp_f32_e32 v91, v91
	ds_read_b128 v[114:117], v189
	ds_read_b128 v[118:121], v189 offset:512
	s_waitcnt lgkmcnt(12)
	v_mfma_f32_32x32x16_bf16 v[4:19], v[156:159], v[124:127], v[4:19]
	v_exp_f32_e32 v92, v92
	v_exp_f32_e32 v93, v93
	v_exp_f32_e32 v94, v94
	v_exp_f32_e32 v95, v95
	ds_read_b128 v[122:125], v189 offset:2048
	ds_read_b128 v[126:129], v189 offset:2560
	s_waitcnt lgkmcnt(12)
	v_mfma_f32_32x32x16_bf16 v[20:35], v[156:159], v[106:109], v[20:35]
	v_exp_f32_e32 v96, v96
	v_exp_f32_e32 v97, v97
	v_exp_f32_e32 v98, v98
	v_exp_f32_e32 v99, v99
	ds_read_b128 v[106:109], v189 offset:4096
	ds_read_b128 v[164:167], v189 offset:4608
	s_waitcnt lgkmcnt(12)
	v_mfma_f32_32x32x16_bf16 v[4:19], v[148:151], v[110:113], v[4:19]
	v_exp_f32_e32 v52, v52
	v_exp_f32_e32 v53, v53
	v_exp_f32_e32 v54, v54
	v_exp_f32_e32 v55, v55
	ds_read_b128 v[110:113], v189 offset:6144
	ds_read_b128 v[100:103], v189 offset:6656
	s_waitcnt lgkmcnt(12)
	v_mfma_f32_32x32x16_bf16 v[20:35], v[148:151], v[68:71], v[20:35]
	v_exp_f32_e32 v56, v56
	v_exp_f32_e32 v57, v57
	v_exp_f32_e32 v58, v58
	v_exp_f32_e32 v59, v59
	s_waitcnt lgkmcnt(10)
	v_mfma_f32_32x32x16_bf16 v[4:19], v[140:143], v[72:75], v[4:19]
	v_exp_f32_e32 v60, v60
	v_exp_f32_e32 v61, v61
	v_exp_f32_e32 v62, v62
	v_exp_f32_e32 v63, v63
	s_waitcnt lgkmcnt(8)
	v_mfma_f32_32x32x16_bf16 v[20:35], v[140:143], v[76:79], v[20:35]
	v_exp_f32_e32 v64, v64
	v_exp_f32_e32 v65, v65
	v_exp_f32_e32 v66, v66
	v_exp_f32_e32 v67, v67
	s_waitcnt vmcnt(0) lgkmcnt(0)
	s_barrier
;   #define RESC() do{ if(resc){ asm volatile("s_waitcnt lgkmcnt(0)":::"memory"); \
;       _Pragma("unroll") for(int d_=0;d_<2;++d_) _Pragma("unroll") for(int r=0;r<16;++r)o[d_][r]*=wsf[crow(r,hi)]; } }while(0)
; template<int THRL,bool NOMAX> __device__ __forceinline__ void attn_unit(int b,int h,int qb,int t0,const bf16*Q,const bf16*__restrict__ KV,const bf16*__restrict__ GA,bf16*O,char*shm){
;     ...
;   STEP(pB0,pB1,pA0,pA1,NT-1,false,false,false); RESC();
	ds_read_b64_tr_b16 v[168:169], v2 offset:40960
	ds_read_b64_tr_b16 v[170:171], v2 offset:41472
	v_add_f32_e32 v68, v84, v85
	v_add_f32_e32 v68, v86, v68
	v_add_f32_e32 v68, v87, v68
	v_add_f32_e32 v68, v88, v68
	v_add_f32_e32 v105, v89, v68
	v_cvt_pk_bf16_f32 v160, v84, v85
	v_cvt_pk_bf16_f32 v161, v86, v87
	s_waitcnt lgkmcnt(9)
	v_mfma_f32_32x32x16_bf16 v[68:83], v[114:117], v[152:155], v[36:51]
	ds_read_b64_tr_b16 v[84:85], v2 offset:45056
	ds_read_b64_tr_b16 v[86:87], v2 offset:45568
	s_waitcnt lgkmcnt(10)
	v_mfma_f32_32x32x16_bf16 v[36:51], v[118:121], v[152:155], v[36:51]
	v_add_f32_e32 v105, v90, v105
	v_add_f32_e32 v105, v91, v105
	v_add_f32_e32 v105, v92, v105
	v_add_f32_e32 v105, v93, v105
	v_cvt_pk_bf16_f32 v162, v88, v89
	v_cvt_pk_bf16_f32 v163, v90, v91
	ds_read_b64_tr_b16 v[88:89], v2 offset:41984
	ds_read_b64_tr_b16 v[90:91], v2 offset:42496
	v_add_f32_e32 v105, v94, v105
	v_add_f32_e32 v105, v95, v105
	v_add_f32_e32 v105, v96, v105
	v_add_f32_e32 v105, v97, v105
	v_cvt_pk_bf16_f32 v156, v92, v93
	v_cvt_pk_bf16_f32 v157, v94, v95
	s_waitcnt lgkmcnt(11)
	v_mfma_f32_32x32x16_bf16 v[68:83], v[122:125], v[144:147], v[68:83]
	ds_read_b64_tr_b16 v[92:93], v2 offset:46080
	ds_read_b64_tr_b16 v[94:95], v2 offset:46592
	s_waitcnt lgkmcnt(12)
	v_mfma_f32_32x32x16_bf16 v[36:51], v[126:129], v[144:147], v[36:51]
	v_add_f32_e32 v105, v98, v105
	v_add_f32_e32 v105, v99, v105
	v_add_f32_e32 v105, v52, v105
	v_add_f32_e32 v105, v53, v105
	v_cvt_pk_bf16_f32 v158, v96, v97
	v_cvt_pk_bf16_f32 v159, v98, v99
	ds_read_b64_tr_b16 v[96:97], v2 offset:43008
	ds_read_b64_tr_b16 v[98:99], v2 offset:43520
	v_add_f32_e32 v105, v54, v105
	v_add_f32_e32 v105, v55, v105
	v_add_f32_e32 v105, v56, v105
	v_add_f32_e32 v105, v57, v105
	v_cvt_pk_bf16_f32 v148, v52, v53
	v_cvt_pk_bf16_f32 v149, v54, v55
	s_waitcnt lgkmcnt(13)
	v_mfma_f32_32x32x16_bf16 v[68:83], v[106:109], v[136:139], v[68:83]
	ds_read_b64_tr_b16 v[52:53], v2 offset:47104
	ds_read_b64_tr_b16 v[54:55], v2 offset:47616
	s_waitcnt lgkmcnt(14)
	v_mfma_f32_32x32x16_bf16 v[36:51], v[164:167], v[136:139], v[36:51]
	v_add_f32_e32 v105, v58, v105
	v_add_f32_e32 v105, v59, v105
	v_add_f32_e32 v105, v60, v105
	v_add_f32_e32 v105, v61, v105
	v_cvt_pk_bf16_f32 v150, v56, v57
	v_cvt_pk_bf16_f32 v151, v58, v59
	ds_read_b64_tr_b16 v[56:57], v2 offset:44032
	ds_read_b64_tr_b16 v[58:59], v2 offset:44544
	v_add_f32_e32 v105, v62, v105
	v_add_f32_e32 v105, v63, v105
	v_add_f32_e32 v105, v64, v105
	v_add_f32_e32 v105, v65, v105
	v_cvt_pk_bf16_f32 v140, v60, v61
	v_cvt_pk_bf16_f32 v141, v62, v63
	s_waitcnt lgkmcnt(14)
	v_mfma_f32_32x32x16_bf16 v[68:83], v[110:113], v[132:135], v[68:83]
	ds_read_b64_tr_b16 v[60:61], v2 offset:48128
	ds_read_b64_tr_b16 v[62:63], v2 offset:48640
	v_mfma_f32_32x32x16_bf16 v[36:51], v[100:103], v[132:135], v[36:51]
	v_add_f32_e32 v2, v66, v105
	v_add_f32_e32 v2, v67, v2
	v_add_f32_e32 v2, 0, v2
	v_cvt_pk_bf16_f32 v142, v64, v65
	v_cvt_pk_bf16_f32 v143, v66, v67
	s_waitcnt lgkmcnt(14)
	v_mfma_f32_32x32x16_bf16 v[4:19], v[160:163], v[168:171], v[4:19]
	s_nop 1
	v_exp_f32_e32 v68, v68
	v_exp_f32_e32 v69, v69
	v_exp_f32_e32 v70, v70
	v_exp_f32_e32 v71, v71
	s_waitcnt lgkmcnt(12)
	v_mfma_f32_32x32x16_bf16 v[20:35], v[160:163], v[84:87], v[20:35]
	v_exp_f32_e32 v72, v72
	v_exp_f32_e32 v73, v73
	v_exp_f32_e32 v74, v74
	v_exp_f32_e32 v75, v75
	s_waitcnt lgkmcnt(10)
	v_mfma_f32_32x32x16_bf16 v[4:19], v[156:159], v[88:91], v[4:19]
	v_exp_f32_e32 v76, v76
	v_exp_f32_e32 v77, v77
	v_exp_f32_e32 v78, v78
	v_exp_f32_e32 v79, v79
	s_waitcnt lgkmcnt(8)
	v_mfma_f32_32x32x16_bf16 v[20:35], v[156:159], v[92:95], v[20:35]
	v_exp_f32_e32 v80, v80
	v_exp_f32_e32 v81, v81
	v_exp_f32_e32 v82, v82
	v_exp_f32_e32 v83, v83
	s_waitcnt lgkmcnt(6)
; #define SBAR() __builtin_amdgcn_sched_barrier(0)
;   #define RESC() do{ if(resc){ asm volatile("s_waitcnt lgkmcnt(0)":::"memory"); \
;       _Pragma("unroll") for(int d_=0;d_<2;++d_) _Pragma("unroll") for(int r=0;r<16;++r)o[d_][r]*=wsf[crow(r,hi)]; } }while(0)
;   #define PKW(P,B) cvtpk_s(P[B],P[B+1])
; __device__ __forceinline__ void pv(f32x16*o,int vb,bf16x8 pa0,bf16x8 pa1,bf16x8 pa2,bf16x8 pa3){
;   #pragma unroll
;   for(int d0=0;d0<2;++d0){s16x4 lo[4],hi[4];
;     #pragma unroll
;     for(int ks=0;ks<4;++ks){
;       asm volatile("ds_read_b64_tr_b16 %0,%1 offset:%c2":"=&v"(lo[ks]):"v"(vb),"i"(d0*4096+ks*1024):"memory");
;       asm volatile("ds_read_b64_tr_b16 %0,%1 offset:%c2":"=&v"(hi[ks]):"v"(vb),"i"(d0*4096+ks*1024+512):"memory");}
;     asm volatile("s_waitcnt lgkmcnt(0)":::"memory");SBAR();
;     ...
;     o[d0]=__builtin_amdgcn_mfma_f32_32x32x16_bf16(pa0,PK(0),o[d0],0,0,0);
;     o[d0]=__builtin_amdgcn_mfma_f32_32x32x16_bf16(pa1,PK(1),o[d0],0,0,0);
;     o[d0]=__builtin_amdgcn_mfma_f32_32x32x16_bf16(pa2,PK(2),o[d0],0,0,0);
;     o[d0]=__builtin_amdgcn_mfma_f32_32x32x16_bf16(pa3,PK(3),o[d0],0,0,0);
;     ...
;   }
; }
; template<int THRL,bool NOMAX> __device__ __forceinline__ void attn_unit(int b,int h,int qb,int t0,const bf16*Q,const bf16*__restrict__ KV,const bf16*__restrict__ GA,bf16*O,char*shm){
;     ...
;   STEP(pB0,pB1,pA0,pA1,NT-1,false,false,false); RESC();
;   { float sacc=pB0[0]+pB0[1]; _Pragma("unroll") for(int r=2;r<16;++r)sacc+=pB0[r]; _Pragma("unroll") for(int r=0;r<16;++r)sacc+=pB1[r]; l_reg+=sacc;
;     pw0=(u32x4){PKW(pB0,0),PKW(pB0,2),PKW(pB0,4),PKW(pB0,6)};pw1=(u32x4){PKW(pB0,8),PKW(pB0,10),PKW(pB0,12),PKW(pB0,14)};pw2=(u32x4){PKW(pB1,0),PKW(pB1,2),PKW(pB1,4),PKW(pB1,6)};pw3=(u32x4){PKW(pB1,8),PKW(pB1,10),PKW(pB1,12),PKW(pB1,14)};
;     SBAR(); pv(o,vb0+sl_cur,PAF(0),PAF(1),PAF(2),PAF(3)); }
;     ...
;   {auto rr=__builtin_amdgcn_permlane32_swap(__float_as_uint(l_reg),__float_as_uint(l_reg),false,false);l_reg=__uint_as_float(rr[0])+__uint_as_float(rr[1]);}
;   if(hi==0)wsf[32+r32]=l_reg;asm volatile("s_waitcnt lgkmcnt(0)":::"memory");
	v_mfma_f32_32x32x16_bf16 v[4:19], v[148:151], v[96:99], v[4:19]
	v_exp_f32_e32 v36, v36
	v_exp_f32_e32 v37, v37
	v_exp_f32_e32 v38, v38
	v_exp_f32_e32 v39, v39
	s_waitcnt lgkmcnt(4)
	v_mfma_f32_32x32x16_bf16 v[20:35], v[148:151], v[52:55], v[20:35]
	v_exp_f32_e32 v40, v40
	v_exp_f32_e32 v41, v41
	v_exp_f32_e32 v42, v42
	v_exp_f32_e32 v43, v43
	s_waitcnt lgkmcnt(2)
	v_mfma_f32_32x32x16_bf16 v[4:19], v[140:143], v[56:59], v[4:19]
	v_exp_f32_e32 v44, v44
	v_exp_f32_e32 v45, v45
	v_exp_f32_e32 v46, v46
	v_exp_f32_e32 v47, v47
	s_waitcnt lgkmcnt(0)
	v_mfma_f32_32x32x16_bf16 v[20:35], v[140:143], v[60:63], v[20:35]
	v_exp_f32_e32 v48, v48
	v_exp_f32_e32 v49, v49
	v_exp_f32_e32 v50, v50
	v_exp_f32_e32 v51, v51
	v_add_f32_e32 v52, v68, v69
	v_add_f32_e32 v52, v70, v52
	v_add_f32_e32 v52, v71, v52
	v_add_f32_e32 v52, v72, v52
	v_add_f32_e32 v52, v73, v52
	v_add_f32_e32 v52, v74, v52
	v_add_f32_e32 v52, v75, v52
	v_add_f32_e32 v52, v76, v52
	v_add_f32_e32 v52, v77, v52
	v_add_f32_e32 v52, v78, v52
	v_add_f32_e32 v52, v79, v52
	v_add_f32_e32 v52, v80, v52
	v_add_f32_e32 v52, v81, v52
	v_add_f32_e32 v52, v82, v52
	v_add_f32_e32 v52, v83, v52
	v_add_f32_e32 v52, v36, v52
	v_add_f32_e32 v52, v37, v52
	v_add_f32_e32 v52, v38, v52
	v_add_f32_e32 v52, v39, v52
	v_add_f32_e32 v52, v40, v52
	v_add_f32_e32 v52, v41, v52
	v_add_f32_e32 v52, v42, v52
	v_add_f32_e32 v52, v43, v52
	v_add_f32_e32 v52, v44, v52
	v_add_f32_e32 v52, v45, v52
	v_add_f32_e32 v52, v46, v52
	v_add_f32_e32 v52, v47, v52
	v_add_f32_e32 v52, v48, v52
	v_add_f32_e32 v52, v49, v52
	v_add_f32_e32 v52, v50, v52
	v_add_f32_e32 v52, v51, v52
	v_add_f32_e32 v2, v104, v2
	v_add_f32_e32 v2, v2, v52
	v_cvt_pk_bf16_f32 v36, v36, v37
	v_cvt_pk_bf16_f32 v52, v68, v69
	v_cvt_pk_bf16_f32 v53, v70, v71
	v_cvt_pk_bf16_f32 v54, v72, v73
	v_cvt_pk_bf16_f32 v55, v74, v75
	v_cvt_pk_bf16_f32 v56, v76, v77
	v_cvt_pk_bf16_f32 v57, v78, v79
	v_cvt_pk_bf16_f32 v58, v80, v81
	v_cvt_pk_bf16_f32 v59, v82, v83
	v_cvt_pk_bf16_f32 v37, v38, v39
	v_cvt_pk_bf16_f32 v38, v40, v41
	v_cvt_pk_bf16_f32 v39, v42, v43
	v_cvt_pk_bf16_f32 v40, v44, v45
	v_cvt_pk_bf16_f32 v41, v46, v47
	v_cvt_pk_bf16_f32 v42, v48, v49
	v_cvt_pk_bf16_f32 v43, v50, v51
	ds_read_b64_tr_b16 v[44:45],v190 offset:0
	ds_read_b64_tr_b16 v[46:47],v190 offset:512
	ds_read_b64_tr_b16 v[48:49],v190 offset:1024
	ds_read_b64_tr_b16 v[50:51],v190 offset:1536
	ds_read_b64_tr_b16 v[60:61],v190 offset:2048
	ds_read_b64_tr_b16 v[62:63],v190 offset:2560
	ds_read_b64_tr_b16 v[64:65],v190 offset:3072
	ds_read_b64_tr_b16 v[66:67],v190 offset:3584
	s_waitcnt lgkmcnt(0)
	s_nop 0
	v_mfma_f32_32x32x16_bf16 v[4:19], v[52:55], v[44:47], v[4:19]
	ds_read_b64_tr_b16 v[44:45],v190 offset:4096
	ds_read_b64_tr_b16 v[46:47],v190 offset:4608
	v_mfma_f32_32x32x16_bf16 v[4:19], v[56:59], v[48:51], v[4:19]
	ds_read_b64_tr_b16 v[48:49],v190 offset:5120
	ds_read_b64_tr_b16 v[50:51],v190 offset:5632
	v_mfma_f32_32x32x16_bf16 v[4:19], v[36:39], v[60:63], v[4:19]
	ds_read_b64_tr_b16 v[60:61],v190 offset:6144
	ds_read_b64_tr_b16 v[62:63],v190 offset:6656
	v_mfma_f32_32x32x16_bf16 v[4:19], v[40:43], v[64:67], v[4:19]
	ds_read_b64_tr_b16 v[64:65],v190 offset:7168
	ds_read_b64_tr_b16 v[66:67],v190 offset:7680
	s_waitcnt lgkmcnt(0)
	v_mfma_f32_32x32x16_bf16 v[20:35], v[52:55], v[44:47], v[20:35]
	v_cmp_gt_u32_e32 vcc, 32, v184
	v_mfma_f32_32x32x16_bf16 v[20:35], v[56:59], v[48:51], v[20:35]
	v_mfma_f32_32x32x16_bf16 v[20:35], v[36:39], v[60:63], v[20:35]
	v_mov_b32_e32 v36, v2
	s_nop 1
	v_permlane32_swap_b32_e32 v2, v36
	v_mfma_f32_32x32x16_bf16 v[20:35], v[40:43], v[64:67], v[20:35]
	s_and_saveexec_b64 s[8:9], vcc
	s_cbranch_execz .LBB0_470
	v_lshl_add_u32 v37, v185, 2, s12
	v_add_f32_e32 v2, v2, v36
	ds_write_b32 v37, v2 offset:49280
	s_branch .LBB0_470
